# GLA scan: waves 0-3 raise s_setprio while computing the intra-chunk matrix (concurrent with waves 4-7 qe@S MFMAs on the same SIMDs)
# baseline (speedup 1.0000x reference)
; __device__ __forceinline__ unsigned pk2(float lo, float hi) { f32x2_t v = {lo, hi}; bf16x2_t b = __builtin_convertvector(v, bf16x2_t); return __builtin_bit_cast(unsigned, b); }
; #define OPAQUE_TID(name) int name = MK_TID; asm volatile("" : "+v"(name))
; __device__ __forceinline__ void scan_unit(const int unit, const Args& a, unsigned char* lds, const int mk_wid) {
;     ...
;             if (wid < 4) { OPAQUE_TID(t_); const int r32 = t_ & 31, hi = (t_ >> 5) & 1;
;                 const int jt = wid >> 1, it = wid & 1; f32x16 ct = f32x16{};
;                 const u16* kp = ke + (jt * 32 + r32) * QP + hi * 8; const u16* qp = qe + (it * 32 + r32) * QP + hi * 8;
; #pragma unroll
;                 for (int kb = 0; kb < 8; ++kb) ct = __builtin_amdgcn_mfma_f32_32x32x16_bf16(*(const bf16x8*)(kp + kb * 16), *(const bf16x8*)(qp + kb * 16), ct, 0, 0, 0);
;                 const int i = it * 32 + r32;
; #pragma unroll
;                 for (int rg = 0; rg < 4; ++rg) { const int j0 = jt * 32 + 8 * rg + 4 * hi;
;                     const float x0 = (j0 + 0 <= i) ? ct[4 * rg + 0] : 0.f, x1 = (j0 + 1 <= i) ? ct[4 * rg + 1] : 0.f, x2 = (j0 + 2 <= i) ? ct[4 * rg + 2] : 0.f, x3 = (j0 + 3 <= i) ? ct[4 * rg + 3] : 0.f;
;                     v2u w; w.x = pk2(x0, x1); w.y = pk2(x2, x3); *(v2u*)(am + i * AP + j0) = w; } }
;             __syncthreads();
.Lscan_pf_nolr:
.LBB0_435:
	s_cmp_gt_u32 s5, 3
	s_cselect_b32 s4, 39, 3
	s_add_i32 s4, s4, s50
	s_sub_i32 s4, s4, 38
	s_and_b64 s[26:27], s[2:3], exec
	s_cselect_b32 s42, s5, s4
	s_cmp_gt_i32 s42, 3
	s_cselect_b64 s[26:27], -1, 0
	s_cmp_lt_i32 s42, 4
	s_cselect_b64 s[34:35], -1, 0
	s_and_b64 vcc, exec, s[34:35]
	s_waitcnt lgkmcnt(0)
	s_barrier
	s_cbranch_vccnz .LBB0_439
	s_andn2_b64 vcc, exec, s[24:25]
	s_cbranch_vccnz .LBB0_438
	s_setprio 3
	v_mbcnt_lo_u32_b32 v64, -1, 0
	v_mbcnt_hi_u32_b32 v64, -1, v64
	s_nop 0
	v_add_u32_e32 v64, s72, v64
	s_nop 0
	v_and_b32_e32 v68, 31, v64
	v_bfe_u32 v154, v64, 5, 1
	v_or_b32_e32 v64, s46, v68
	v_mul_lo_u32 v64, v64, s51
	v_lshlrev_b32_e32 v69, 4, v154
	v_add3_u32 v157, 0, v64, v69
	v_or_b32_e32 v158, s47, v68
	v_mul_u32_u24_e32 v68, 0x110, v158
	v_add3_u32 v159, 0, v68, v69
	ds_read_b128 v[170:173], v157 offset:17408
	ds_read_b128 v[174:177], v159
	ds_read_b128 v[178:181], v157 offset:17440
	ds_read_b128 v[182:185], v159 offset:32
	ds_read_b128 v[186:189], v157 offset:17472
	ds_read_b128 v[190:193], v159 offset:64
	ds_read_b128 v[194:197], v157 offset:17504
	ds_read_b128 v[198:201], v159 offset:96
	ds_read_b128 v[202:205], v157 offset:17536
	ds_read_b128 v[206:209], v159 offset:128
	ds_read_b128 v[210:213], v157 offset:17568
	ds_read_b128 v[214:217], v159 offset:160
	ds_read_b128 v[218:221], v157 offset:17600
	ds_read_b128 v[222:225], v159 offset:192
	ds_read_b128 v[226:229], v157 offset:17632
	v_lshl_or_b32 v154, v154, 2, s46
	v_cmp_le_u32_e32 vcc, v154, v158
	v_or_b32_e32 v161, 2, v154
	v_or_b32_e32 v162, 3, v154
	v_or_b32_e32 v164, 8, v154
	v_mul_u32_u24_e32 v160, 0x90, v158
	v_lshlrev_b32_e32 v163, 1, v154
	s_waitcnt lgkmcnt(13)
	v_mfma_f32_32x32x16_bf16 v[64:79], v[170:173], v[174:177], 0
	ds_read_b128 v[230:233], v159 offset:224
	v_or_b32_e32 v80, 10, v154
	v_or_b32_e32 v81, 11, v154
	v_or_b32_e32 v82, 16, v154
	v_or_b32_e32 v83, 18, v154
	v_or_b32_e32 v84, 19, v154
	v_or_b32_e32 v85, 24, v154
	v_add3_u32 v86, s57, v160, v163
	s_waitcnt lgkmcnt(12)
	v_mfma_f32_32x32x16_bf16 v[64:79], v[178:181], v[182:185], v[64:79]
	s_waitcnt lgkmcnt(10)
	v_mfma_f32_32x32x16_bf16 v[64:79], v[186:189], v[190:193], v[64:79]
	s_waitcnt lgkmcnt(8)
	v_mfma_f32_32x32x16_bf16 v[64:79], v[194:197], v[198:201], v[64:79]
	s_waitcnt lgkmcnt(6)
	v_mfma_f32_32x32x16_bf16 v[64:79], v[202:205], v[206:209], v[64:79]
	s_waitcnt lgkmcnt(4)
	v_mfma_f32_32x32x16_bf16 v[64:79], v[210:213], v[214:217], v[64:79]
	s_waitcnt lgkmcnt(2)
	v_mfma_f32_32x32x16_bf16 v[64:79], v[218:221], v[222:225], v[64:79]
	s_waitcnt lgkmcnt(0)
	v_mfma_f32_32x32x16_bf16 v[64:79], v[226:229], v[230:233], v[64:79]
	s_nop 11
	v_cndmask_b32_e32 v64, 0, v64, vcc
	v_cmp_lt_u32_e32 vcc, v154, v158
	s_nop 1
	v_cndmask_b32_e32 v65, 0, v65, vcc
	v_cmp_le_u32_e32 vcc, v161, v158
	v_cvt_pk_bf16_f32 v64, v64, v65
	s_nop 0
	v_cndmask_b32_e32 v66, 0, v66, vcc
	v_cmp_le_u32_e32 vcc, v162, v158
	s_nop 1
	v_cndmask_b32_e32 v67, 0, v67, vcc
	v_cmp_le_u32_e32 vcc, v164, v158
	v_cvt_pk_bf16_f32 v65, v66, v67
	s_nop 0
	v_cndmask_b32_e32 v68, 0, v68, vcc
	v_cmp_lt_u32_e32 vcc, v164, v158
	s_nop 1
	v_cndmask_b32_e32 v69, 0, v69, vcc
	v_cmp_le_u32_e32 vcc, v80, v158
	v_cvt_pk_bf16_f32 v66, v68, v69
	s_nop 0
	v_cndmask_b32_e32 v70, 0, v70, vcc
	v_cmp_le_u32_e32 vcc, v81, v158
	s_nop 1
	v_cndmask_b32_e32 v71, 0, v71, vcc
	v_cmp_le_u32_e32 vcc, v82, v158
	v_cvt_pk_bf16_f32 v67, v70, v71
	ds_write2_b64 v86, v[64:65], v[66:67] offset1:2
	v_cndmask_b32_e32 v72, 0, v72, vcc
	v_cmp_lt_u32_e32 vcc, v82, v158
	v_or_b32_e32 v65, 26, v154
	v_or_b32_e32 v66, 27, v154
	v_cndmask_b32_e32 v73, 0, v73, vcc
	v_cmp_le_u32_e32 vcc, v83, v158
	v_cvt_pk_bf16_f32 v68, v72, v73
	s_nop 0
	v_cndmask_b32_e32 v74, 0, v74, vcc
	v_cmp_le_u32_e32 vcc, v84, v158
	s_nop 1
	v_cndmask_b32_e32 v75, 0, v75, vcc
	v_cmp_le_u32_e32 vcc, v85, v158
	v_cvt_pk_bf16_f32 v69, v74, v75
	s_nop 0
	v_cndmask_b32_e32 v76, 0, v76, vcc
	v_cmp_lt_u32_e32 vcc, v85, v158
	s_nop 1
	v_cndmask_b32_e32 v64, 0, v77, vcc
	v_cmp_le_u32_e32 vcc, v65, v158
	v_cvt_pk_bf16_f32 v64, v76, v64
	s_nop 0
	v_cndmask_b32_e32 v65, 0, v78, vcc
	v_cmp_le_u32_e32 vcc, v66, v158
	s_nop 1
	v_cndmask_b32_e32 v66, 0, v79, vcc
	v_cvt_pk_bf16_f32 v65, v65, v66
	ds_write2_b64 v86, v[68:69], v[64:65] offset0:4 offset1:6
	s_setprio 0
